# LN GEMM epilogues: redundant L1 invalidate after the row-statistics poll removed (slot reads are L1-bypassing), on top of the gamma/beta hoist
# baseline (speedup 1.0000x reference)
.LBB0_1769:
	s_waitcnt vmcnt(0)

	s_and_b64 exec, exec, s[44:45]
	s_cbranch_execz .LBB0_1771
	v_readlane_b32 s12, v252, 13
	v_cndmask_b32_e64 v66, 0, 1, s[46:47]
	s_nop 0
	v_mov_b32_e32 v67, s12
	ds_write_b32 v67, v66

.LBB0_2030:
	v_readlane_b32 s74, v252, 21
	v_readlane_b32 s75, v252, 22
	s_and_saveexec_b64 s[70:71], s[12:13]
	s_cbranch_execz .LBB0_2033
	s_waitcnt vmcnt(0)

	s_and_b64 exec, exec, s[44:45]
	s_cbranch_execz .LBB0_2033
	v_readlane_b32 s3, v252, 13
	v_cndmask_b32_e64 v66, 0, 1, s[46:47]
	s_nop 0
	v_mov_b32_e32 v67, s3
	ds_write_b32 v67, v66
